# v18 + GEMM2 split wait: K slices 0..9 start when the 10 non-MLA units of the token block are done (new partial counter), MLA columns awaited mid K loop
# speedup vs baseline: 1.0066x; 1.0066x over previous
.LBB0_173:
	v_writelane_b32 v185, s5, 0
	s_cmpk_lt_i32 s5, 0x60
	s_cselect_b64 s[28:29], -1, 0
	s_cmpk_gt_i32 s5, 0x5f
	s_cselect_b64 s[34:35], -1, 0
	s_add_i32 s11, s5, 0xffffff00
	s_cmpk_lt_u32 s11, 0x60
	s_cselect_b64 s[2:3], -1, 0
	s_or_b64 s[2:3], s[28:29], s[2:3]
	s_andn2_b64 vcc, exec, s[2:3]
	s_cbranch_vccz .LBB0_180
	s_cmpk_lt_u32 s5, 0xc0
	s_cselect_b64 s[44:45], -1, 0
	s_cmpk_gt_u32 s5, 0xbf
	s_cselect_b64 s[46:47], -1, 0
	s_and_b64 vcc, exec, s[46:47]
	s_cbranch_vccz .LBB0_181
	s_add_i32 s0, s5, 0xfffffea0
	s_cmpk_lt_u32 s0, 0x60
	s_cselect_b64 s[48:49], -1, 0
	s_cmpk_gt_u32 s0, 0x5f
	s_mov_b64 s[40:41], 0
	s_cbranch_scc0 .LBB0_265
	s_load_dwordx2 s[2:3], s[86:87], 0x68
	v_readlane_b32 s0, v254, 19
	v_readlane_b32 s1, v254, 20
	s_lshl_b64 s[36:37], s[0:1], 2
	s_waitcnt lgkmcnt(0)
	s_add_u32 s52, s2, s36
	s_addc_u32 s53, s3, s37
	s_cmpk_lt_u32 s5, 0x100
	s_cselect_b64 s[58:59], -1, 0
	s_cmpk_gt_u32 s5, 0xff
	s_cselect_b64 s[56:57], -1, 0
	s_and_b64 vcc, exec, s[56:57]
	s_cbranch_vccz .LBB0_194
	s_and_b32 s0, s5, 0x7fffffc0
	s_cmpk_lg_i32 s0, 0x1c0
	s_cbranch_scc0 .LBB0_195
	s_and_b32 s3, s5, 3
	s_lshl_b32 s0, s3, 2
	v_mov_b32_e32 v0, s0
	global_load_dword v3, v0, s[52:53]
	global_load_dword v2, v0, s[52:53] offset:16
	s_add_i32 s0, s5, 0xfffffe00
	s_and_b32 s2, s0, -4
	v_readlane_b32 s36, v254, 10
	s_andn2_b64 vcc, exec, s[12:13]
	s_add_i32 s2, s2, s36
	v_readlane_b32 s37, v254, 11
	s_cbranch_vccnz .LBB0_199
	v_readlane_b32 s36, v254, 10
	s_mul_i32 s33, s36, 0x7f
	v_readlane_b32 s37, v254, 11
	s_add_i32 s36, s2, s33
	s_ashr_i32 s37, s36, 31
	s_lshl_b64 s[36:37], s[36:37], 2
	v_readlane_b32 s1, v254, 59
	v_mov_b32_e32 v4, v205
	s_add_u32 s36, s1, s36
	v_readlane_b32 s1, v254, 60
	s_addc_u32 s37, s1, s37
	v_lshlrev_b32_e32 v0, 2, v4
	v_ashrrev_i32_e32 v1, 31, v0
	v_lshl_add_u64 v[0:1], v[0:1], 2, s[36:37]
	s_mov_b32 s33, 1
	v_cmp_gt_i32_e64 s[40:41], 1, v4
	v_readlane_b32 s100, v254, 59
	s_lshl_b32 s101, s79, 4
	s_add_i32 s100, s100, s101
	v_subrev_u32_e32 v179, s100, v0
	v_lshrrev_b32_e32 v179, 2, v179
	ds_bpermute_b32 v179, v179, v178
	s_waitcnt lgkmcnt(0)
	v_cmp_gt_u32_e32 vcc, 8, v179
	s_and_b64 vcc, vcc, s[40:41]
	s_cbranch_vccz .LBB0_199
	s_mov_b64 s[62:63], 0
	s_branch .LBB0_184

.LBB0_355:
	s_and_saveexec_b64 s[2:3], s[40:41]
	s_xor_b64 s[28:29], exec, s[2:3]
	s_cbranch_execz .LBB0_154
	v_mov_b64_e32 v[0:1], s[64:65]
	global_atomic_add v[0:1], v181, off
	v_readlane_b32 s100, v185, 0
	s_sub_u32 s101, s100, 0x60
	s_cmpk_lt_u32 s101, 0xa0
	s_cbranch_scc1 .Lypart_add
	s_sub_u32 s101, s100, 0x160
	s_cmpk_lt_u32 s101, 0xa0
	s_cbranch_scc0 .LBB0_154
.Lypart_add:
	global_atomic_add v[0:1], v181, off offset:4
	s_branch .LBB0_154

.LBB0_365:
	s_and_b32 s73, s72, 31
	s_and_saveexec_b64 s[16:17], s[38:39]
	s_cbranch_execz .LBB0_392
	s_lshl_b32 s0, s73, 2
	v_readlane_b32 s18, v254, 28
	v_readlane_b32 s19, v254, 29
	s_or_b32 s18, s0, s18
	s_ashr_i32 s19, s18, 31
	s_lshl_b64 s[18:19], s[18:19], 2
	v_readlane_b32 s26, v252, 29
	v_readlane_b32 s27, v252, 30
	s_add_u32 s18, s26, s18
	s_addc_u32 s19, s27, s19
	v_mov_b32_e32 v176, s18
	v_mov_b32_e32 v177, s19
	global_load_dword v0, v81, s[18:19] offset:4 sc1
	s_waitcnt vmcnt(0)
	v_cmp_lt_u32_e32 vcc, 9, v0
	s_cbranch_vccnz .LBB0_379
	s_mov_b32 s0, 1
	s_branch .LBB0_369

.LBB0_371:
	global_load_dword v0, v81, s[18:19] offset:4 sc1
	s_add_i32 s0, s0, 1
	s_mov_b64 s[28:29], -1
	s_waitcnt vmcnt(0)
	v_cmp_lt_u32_e64 s[26:27], 9, v0
	s_branch .LBB0_368

.LBB0_393:
	s_and_b32 s0, s28, 1
	s_xor_b32 s29, s0, 1
	s_mul_i32 s29, s29, 0xc000
	s_add_i32 s34, s52, s29
	v_lshl_add_u64 v[94:95], v[92:93], 0, s[26:27]
	s_mul_i32 s0, s0, 0xc000
	s_add_i32 s29, s50, s29
	s_mov_b32 m0, s34
	v_lshl_add_u64 v[96:97], v[88:89], 0, s[26:27]
	s_add_i32 s0, s0, 0
	global_load_lds_dwordx4 v[94:95], off
	s_add_i32 m0, s29, 0x4000
	v_lshl_add_u64 v[98:99], v[86:87], 0, s[26:27]
	v_add_u32_e32 v80, s0, v153
	v_add_u32_e32 v139, s0, v154
	global_load_lds_dwordx4 v[96:97], off
	s_add_i32 m0, s29, 0x4400
	v_add_u32_e32 v146, v80, v151
	v_add_u32_e32 v110, v139, v151
	global_load_lds_dwordx4 v[98:99], off
	ds_read_b128 v[94:97], v146
	ds_read_b128 v[98:101], v110 offset:16384
	ds_read_b128 v[102:105], v110 offset:18432
	ds_read_b128 v[106:109], v110 offset:20480
	ds_read_b128 v[110:113], v110 offset:22528
	s_waitcnt lgkmcnt(0)
	v_mfma_f32_16x16x32_bf16 v[76:79], v[94:97], v[98:101], v[76:79]
	v_lshl_add_u64 v[140:141], v[90:91], 0, s[26:27]
	s_add_i32 s0, s29, 0x4800
	s_add_i32 m0, s34, 0x400
	v_mfma_f32_16x16x32_bf16 v[72:75], v[94:97], v[102:105], v[72:75]
	v_lshl_add_u64 v[142:143], v[82:83], 0, s[26:27]
	s_addk_i32 s29, 0x4c00
	v_lshl_add_u64 v[144:145], v[84:85], 0, s[26:27]
	v_mfma_f32_16x16x32_bf16 v[68:71], v[94:97], v[106:109], v[68:71]
	v_add_u32_e32 v80, v80, v152
	v_add_u32_e32 v139, v139, v152
	s_add_i32 s28, s28, 1
	v_mfma_f32_16x16x32_bf16 v[64:67], v[94:97], v[110:113], v[64:67]
	ds_read_b128 v[94:97], v146 offset:2048
	s_add_u32 s26, s26, 0x80
	s_addc_u32 s27, s27, 0
	s_waitcnt lgkmcnt(0)
	v_mfma_f32_16x16x32_bf16 v[60:63], v[94:97], v[98:101], v[60:63]
	s_cmpk_eq_i32 s26, 0x780
	v_mfma_f32_16x16x32_bf16 v[56:59], v[94:97], v[102:105], v[56:59]
	v_mfma_f32_16x16x32_bf16 v[52:55], v[94:97], v[106:109], v[52:55]
	v_mfma_f32_16x16x32_bf16 v[48:51], v[94:97], v[110:113], v[48:51]
	ds_read_b128 v[94:97], v146 offset:4096
	s_waitcnt lgkmcnt(0)
	v_mfma_f32_16x16x32_bf16 v[44:47], v[94:97], v[98:101], v[44:47]
	v_mfma_f32_16x16x32_bf16 v[40:43], v[94:97], v[102:105], v[40:43]
	v_mfma_f32_16x16x32_bf16 v[32:35], v[94:97], v[106:109], v[32:35]
	v_mfma_f32_16x16x32_bf16 v[24:27], v[94:97], v[110:113], v[24:27]
	ds_read_b128 v[94:97], v146 offset:6144
	global_load_lds_dwordx4 v[140:141], off
	s_mov_b32 m0, s0
	s_waitcnt lgkmcnt(0)
	v_mfma_f32_16x16x32_bf16 v[20:23], v[94:97], v[98:101], v[20:23]
	global_load_lds_dwordx4 v[142:143], off
	s_mov_b32 m0, s29
	v_mfma_f32_16x16x32_bf16 v[16:19], v[94:97], v[102:105], v[16:19]
	global_load_lds_dwordx4 v[144:145], off
	ds_read_b128 v[98:101], v80
	v_mfma_f32_16x16x32_bf16 v[36:39], v[94:97], v[106:109], v[36:39]
	ds_read_b128 v[102:105], v139 offset:18432
	ds_read_b128 v[106:109], v139 offset:20480
	v_mfma_f32_16x16x32_bf16 v[28:31], v[94:97], v[110:113], v[28:31]
	ds_read_b128 v[94:97], v139 offset:16384
	ds_read_b128 v[110:113], v139 offset:22528
	s_waitcnt lgkmcnt(0)
	v_mfma_f32_16x16x32_bf16 v[76:79], v[98:101], v[94:97], v[76:79]
	v_mfma_f32_16x16x32_bf16 v[72:75], v[98:101], v[102:105], v[72:75]
	v_mfma_f32_16x16x32_bf16 v[68:71], v[98:101], v[106:109], v[68:71]
	v_mfma_f32_16x16x32_bf16 v[64:67], v[98:101], v[110:113], v[64:67]
	ds_read_b128 v[98:101], v80 offset:2048
	s_waitcnt lgkmcnt(0)
	v_mfma_f32_16x16x32_bf16 v[60:63], v[98:101], v[94:97], v[60:63]
	v_mfma_f32_16x16x32_bf16 v[56:59], v[98:101], v[102:105], v[56:59]
	v_mfma_f32_16x16x32_bf16 v[52:55], v[98:101], v[106:109], v[52:55]
	v_mfma_f32_16x16x32_bf16 v[48:51], v[98:101], v[110:113], v[48:51]
	ds_read_b128 v[98:101], v80 offset:4096
	s_waitcnt lgkmcnt(0)
	v_mfma_f32_16x16x32_bf16 v[44:47], v[98:101], v[94:97], v[44:47]
	v_mfma_f32_16x16x32_bf16 v[40:43], v[98:101], v[102:105], v[40:43]
	v_mfma_f32_16x16x32_bf16 v[32:35], v[98:101], v[106:109], v[32:35]
	v_mfma_f32_16x16x32_bf16 v[24:27], v[98:101], v[110:113], v[24:27]
	ds_read_b128 v[98:101], v80 offset:6144
	s_cmpk_lg_i32 s26, 0x480
	s_cbranch_scc1 .Lg2_mid_done
	s_mov_b64 s[100:101], exec
	s_mov_b64 exec, s[38:39]
	s_cbranch_execz .Lg2_mid_rest
	v_mov_b32_e32 v190, 0
.Lg2_mid_spin:
	global_load_dword v189, v[176:177], off sc1
	s_waitcnt vmcnt(0)
	v_cmp_lt_u32_e32 vcc, 15, v189
	s_cbranch_vccnz .Lg2_mid_rest
	v_add_u32_e32 v190, 1, v190
	v_cmp_lt_u32_e32 vcc, 0x80000, v190
	s_cbranch_vccnz .Lg2_mid_rest
	s_sleep 1
	s_branch .Lg2_mid_spin
.Lg2_mid_rest:
	s_mov_b64 exec, s[100:101]
.Lg2_mid_done:
	s_cmpk_eq_i32 s26, 0x780
	s_waitcnt vmcnt(0)
	s_waitcnt vmcnt(0) lgkmcnt(0)
	v_mfma_f32_16x16x32_bf16 v[20:23], v[98:101], v[94:97], v[20:23]
	s_barrier
	v_mfma_f32_16x16x32_bf16 v[16:19], v[98:101], v[102:105], v[16:19]
	v_mfma_f32_16x16x32_bf16 v[36:39], v[98:101], v[106:109], v[36:39]
	v_mfma_f32_16x16x32_bf16 v[28:31], v[98:101], v[110:113], v[28:31]
	s_cbranch_scc0 .LBB0_393
	v_add_u32_e32 v80, v155, v151
	ds_read_b128 v[82:85], v80 offset:49152
	v_add_u32_e32 v110, v156, v151
	ds_read_b128 v[86:89], v110 offset:16384
	ds_read_b128 v[90:93], v80 offset:51200
	ds_read_b128 v[94:97], v110 offset:18432
	ds_read_b128 v[98:101], v80 offset:53248
	ds_read_b128 v[102:105], v110 offset:20480
	ds_read_b128 v[106:109], v80 offset:55296
	ds_read_b128 v[110:113], v110 offset:22528
	s_waitcnt lgkmcnt(5)
	v_mfma_f32_16x16x32_bf16 v[60:63], v[90:93], v[86:89], v[60:63]
	s_or_b32 s26, s19, s54
	s_lshl_b32 s0, s73, 8
	s_ashr_i32 s27, s26, 31
	s_waitcnt lgkmcnt(3)
	v_mfma_f32_16x16x32_bf16 v[44:47], v[98:101], v[86:89], v[44:47]
	v_mov_b32_e32 v139, v188
	s_add_i32 s28, s0, s51
	s_lshl_b64 s[34:35], s[26:27], 1
	v_mfma_f32_16x16x32_bf16 v[76:79], v[82:85], v[86:89], v[76:79]
	s_add_u32 s40, s55, s34
	s_addc_u32 s41, s56, s35
	s_ashr_i32 s29, s28, 31
	s_waitcnt lgkmcnt(1)
	v_mfma_f32_16x16x32_bf16 v[86:89], v[106:109], v[86:89], v[20:23]
	s_and_b64 vcc, exec, s[8:9]
	s_nop 1
	v_add_u32_e32 v20, v155, v152
	v_mfma_f32_16x16x32_bf16 v[144:147], v[106:109], v[94:97], v[16:19]
	v_add_u32_e32 v21, v156, v152
	s_nop 1
	ds_read_b128 v[16:19], v20 offset:49152
	v_mfma_f32_16x16x32_bf16 v[72:75], v[82:85], v[94:97], v[72:75]
	v_mfma_f32_16x16x32_bf16 v[140:143], v[82:85], v[102:105], v[68:71]
	s_waitcnt lgkmcnt(1)
	v_mfma_f32_16x16x32_bf16 v[82:85], v[82:85], v[110:113], v[64:67]
	v_mfma_f32_16x16x32_bf16 v[56:59], v[90:93], v[94:97], v[56:59]
	v_mfma_f32_16x16x32_bf16 v[52:55], v[90:93], v[102:105], v[52:55]
	v_mfma_f32_16x16x32_bf16 v[48:51], v[90:93], v[110:113], v[48:51]
	v_mfma_f32_16x16x32_bf16 v[40:43], v[98:101], v[94:97], v[40:43]
	v_mfma_f32_16x16x32_bf16 v[32:35], v[98:101], v[102:105], v[32:35]
	v_mfma_f32_16x16x32_bf16 v[98:101], v[98:101], v[110:113], v[24:27]
	v_mfma_f32_16x16x32_bf16 v[36:39], v[106:109], v[102:105], v[36:39]
	v_mfma_f32_16x16x32_bf16 v[102:105], v[106:109], v[110:113], v[28:31]
	ds_read_b128 v[94:97], v21 offset:16384
	ds_read_b128 v[24:27], v20 offset:51200
	ds_read_b128 v[106:109], v21 offset:18432
	ds_read_b128 v[110:113], v20 offset:53248
	ds_read_b128 v[158:161], v21 offset:20480
	ds_read_b128 v[162:165], v20 offset:55296
	ds_read_b128 v[166:169], v21 offset:22528
	s_waitcnt vmcnt(0)
	s_waitcnt lgkmcnt(0)
	v_mfma_f32_16x16x32_bf16 v[68:71], v[16:19], v[94:97], v[76:79]
	s_barrier
	v_mfma_f32_16x16x32_bf16 v[64:67], v[16:19], v[106:109], v[72:75]
	v_mfma_f32_16x16x32_bf16 v[20:23], v[16:19], v[158:161], v[140:143]
	v_mfma_f32_16x16x32_bf16 v[16:19], v[16:19], v[166:169], v[82:85]
	s_nop 1
	v_ashrrev_i32_e32 v140, 3, v139
	v_ashrrev_i32_e32 v141, 31, v140
	v_mfma_f32_16x16x32_bf16 v[76:79], v[24:27], v[94:97], v[60:63]
	v_mfma_f32_16x16x32_bf16 v[72:75], v[24:27], v[106:109], v[56:59]
	v_mfma_f32_16x16x32_bf16 v[28:31], v[24:27], v[158:161], v[52:55]
	v_mfma_f32_16x16x32_bf16 v[24:27], v[24:27], v[166:169], v[48:51]
	v_mfma_f32_16x16x32_bf16 v[90:93], v[110:113], v[94:97], v[44:47]
	v_mfma_f32_16x16x32_bf16 v[82:85], v[110:113], v[106:109], v[40:43]
	v_mfma_f32_16x16x32_bf16 v[40:43], v[110:113], v[158:161], v[32:35]
	v_mfma_f32_16x16x32_bf16 v[32:35], v[110:113], v[166:169], v[98:101]
	v_mfma_f32_16x16x32_bf16 v[94:97], v[162:165], v[94:97], v[86:89]
	v_mfma_f32_16x16x32_bf16 v[86:89], v[162:165], v[106:109], v[144:147]
	v_mfma_f32_16x16x32_bf16 v[44:47], v[162:165], v[158:161], v[36:39]
	v_and_b32_e32 v159, 7, v139
	v_lshlrev_b32_e32 v80, 4, v159
	v_lshl_add_u64 v[142:143], s[40:41], 0, v[80:81]
	v_mfma_f32_16x16x32_bf16 v[36:39], v[162:165], v[166:169], v[102:105]
	s_lshl_b64 s[40:41], s[28:29], 11
	v_lshl_add_u64 v[144:145], v[142:143], 0, s[40:41]
	s_mov_b64 s[40:41], -1
	s_mov_b32 s100, 0
	s_cbranch_vccz .LBB0_396
	v_lshlrev_b64 v[146:147], 11, v[140:141]
	v_lshl_add_u64 v[60:61], v[144:145], 0, v[146:147]
	s_movk_i32 s0, 0x4000
	v_add_co_u32_e32 v52, vcc, s0, v60
	s_mov_b32 s0, 0x8000
	s_nop 0
	v_addc_co_u32_e32 v53, vcc, 0, v61, vcc
	v_add_co_u32_e32 v56, vcc, s0, v60
	s_mov_b32 s0, 0xc000
	s_nop 0
	v_addc_co_u32_e32 v57, vcc, 0, v61, vcc
	global_load_dwordx4 v[48:51], v[60:61], off
	v_add_co_u32_e32 v60, vcc, s0, v60
	global_load_dwordx4 v[52:55], v[52:53], off
	s_nop 0
	v_addc_co_u32_e32 v61, vcc, 0, v61, vcc
	global_load_dwordx4 v[56:59], v[56:57], off
	s_mov_b64 s[40:41], 0
	s_mov_b32 s100, 1
	global_load_dwordx4 v[170:173], v[60:61], off
